# one static s_setprio 1 for workgroups 0-255 (one of the two co-resident workgroups per CU), whole kernel
# baseline (speedup 1.0000x reference)
_Z4mega6Paramsii:
	s_load_dwordx8 s[76:83], s[0:1], 0x100
	s_load_dword s26, s[0:1], 0x128
	s_add_u32 s4, s0, 0x128
	v_writelane_b32 v251, s2, 0
	s_addc_u32 s5, s1, 0
	s_cmp_lt_u32 s2, 0x100
	s_cbranch_scc0 .Lprio_skip
	s_setprio 1
.Lprio_skip:
	v_and_b32_e32 v208, 0x3ff, v0
	v_writelane_b32 v251, s4, 1
	s_waitcnt lgkmcnt(0)
	s_add_u32 s30, s82, 0xee61000
	s_getreg_b32 s3, hwreg(HW_REG_XCC_ID, 0, 4)
	v_mov_b32_e32 v1, v208
	v_writelane_b32 v251, s5, 2
	s_addc_u32 s31, s83, 0
	s_and_b32 s20, s3, 15
	s_nop 0
	v_cmp_eq_u32_e32 vcc, 0, v1
	s_and_saveexec_b64 s[8:9], vcc
	s_cbranch_execz .LBB0_3
	v_mov_b32_e32 v2, 0
	s_mov_b64 s[4:5], exec
	v_mov_b32_e32 v3, v2
	v_mov_b32_e32 v4, v2
	v_mov_b32_e32 v5, v2
	v_mov_b32_e32 v1, 0x10000
	ds_write_b128 v1, v[2:5]
	v_mbcnt_lo_u32_b32 v1, s4, 0
	v_mbcnt_hi_u32_b32 v1, s5, v1
	v_cmp_eq_u32_e32 vcc, 0, v1
	s_and_b64 s[6:7], exec, vcc
	s_mov_b64 exec, s[6:7]
	s_cbranch_execz .LBB0_3
	s_lshl_b32 s6, s20, 8
	s_bcnt1_i32_b64 s4, s[4:5]
	v_mov_b32_e32 v1, s6
	v_mov_b32_e32 v2, s4
	global_atomic_add v1, v2, s[30:31] offset:1024
